# prologue de-serialisation: RWKV chain setup issues its 16 LoRA-weight loads and 11 constant loads back to back and waits once (was 19 serial memory round trips)
# baseline (speedup 1.0000x reference)
; __device__ __forceinline__ unsigned f2bf(float f) { return pk2(f, 0.f) & 0xffffu; }
; __device__ __forceinline__ void rwkv_chain(LAS unsigned char* lds, int cid, const bf16_t* P0, const float* mu, const float* w0, const float* w2, const float* a0, const float* a2, ...
;     ...
;     __syncthreads();
;     for (int e = tid; e < 64 * 64; e += 512) { const int j = e & 63, r = e >> 6;
;         a2B[j * 72 + r] = (bf16_t)f2bf(a2[r * 512 + h * 64 + j]); w2B[j * 72 + r] = (bf16_t)f2bf(w2[(dir * 64 + r) * 512 + h * 64 + j]); }
.LBB0_450:
	s_bfe_u32 s1, s86, 0x30001
	s_lshl_b32 s0, s1, 6
	v_or_b32_e32 v1, s0, v45
	s_load_dwordx2 s[12:13], s[64:65], 0x28
	s_load_dwordx2 s[16:17], s[64:65], 0x30
	s_load_dwordx2 s[10:11], s[64:65], 0x38
	s_load_dwordx2 s[40:41], s[64:65], 0x40
	s_load_dwordx2 s[42:43], s[64:65], 0x48
	s_load_dwordx2 s[36:37], s[64:65], 0x58
	s_load_dwordx2 s[38:39], s[64:65], 0x60
	s_load_dwordx2 s[14:15], s[64:65], 0x68
	v_or_b32_e32 v2, v1, v84
	v_lshlrev_b32_e32 v2, 2, v2
	s_waitcnt vmcnt(0) lgkmcnt(0)
	s_barrier
	s_and_b32 s87, s86, 1
	s_lshl_b32 s2, s87, 15
	s_or_b32 s2, s0, s2
	v_or_b32_e32 v0, s2, v45
	v_or_b32_e32 v148, v1, v84
	v_or_b32_e32 v149, v84, v0
	v_lshlrev_b32_e32 v148, 2, v148
	v_lshlrev_b32_e32 v149, 2, v149
	v_or_b32_e32 v150, v1, v89
	v_or_b32_e32 v151, v89, v0
	v_lshlrev_b32_e32 v150, 2, v150
	v_lshlrev_b32_e32 v151, 2, v151
	v_or_b32_e32 v152, v1, v92
	v_or_b32_e32 v153, v92, v0
	v_lshlrev_b32_e32 v152, 2, v152
	v_lshlrev_b32_e32 v153, 2, v153
	v_or_b32_e32 v154, v1, v95
	v_or_b32_e32 v155, v95, v0
	v_lshlrev_b32_e32 v154, 2, v154
	v_lshlrev_b32_e32 v155, 2, v155
	v_or_b32_e32 v156, v1, v98
	v_or_b32_e32 v157, v98, v0
	v_lshlrev_b32_e32 v156, 2, v156
	v_lshlrev_b32_e32 v157, 2, v157
	v_or_b32_e32 v158, v1, v101
	v_or_b32_e32 v159, v101, v0
	v_lshlrev_b32_e32 v158, 2, v158
	v_lshlrev_b32_e32 v159, 2, v159
	v_or_b32_e32 v160, v1, v104
	v_or_b32_e32 v161, v104, v0
	v_lshlrev_b32_e32 v160, 2, v160
	v_lshlrev_b32_e32 v161, 2, v161
	global_load_dword v148, v148, s[42:43]
	global_load_dword v149, v149, s[10:11]
	global_load_dword v150, v150, s[42:43]
	global_load_dword v151, v151, s[10:11]
	global_load_dword v152, v152, s[42:43]
	global_load_dword v153, v153, s[10:11]
	global_load_dword v154, v154, s[42:43]
	global_load_dword v155, v155, s[10:11]
	global_load_dword v156, v156, s[42:43]
	global_load_dword v157, v157, s[10:11]
	global_load_dword v158, v158, s[42:43]
	global_load_dword v159, v159, s[10:11]
	global_load_dword v160, v160, s[42:43]
	global_load_dword v161, v161, s[10:11]
	s_mov_b64 s[44:45], exec
	v_readlane_b32 s2, v253, 50
	v_readlane_b32 s3, v253, 51
	s_and_b64 s[2:3], s[44:45], s[2:3]
	s_mov_b64 exec, s[2:3]
	s_cbranch_execz .Lrw_setup_l8
	v_or_b32_e32 v1, v1, v107
	v_lshlrev_b32_e32 v1, 2, v1
	v_add_lshl_u32 v0, v107, v0, 2
	global_load_dword v163, v0, s[10:11]
	global_load_dword v162, v1, s[42:43]
.Lrw_setup_l8:
	s_mov_b64 exec, s[44:45]
	s_waitcnt vmcnt(0)
	v_cvt_pk_bf16_f32 v148, v148, v148
	v_cvt_pk_bf16_f32 v149, v149, v149
	ds_write_b16 v87, v148
	ds_write_b16 v88, v149
	v_cvt_pk_bf16_f32 v150, v150, v150
	v_cvt_pk_bf16_f32 v151, v151, v151
	ds_write_b16 v90, v150
	ds_write_b16 v91, v151
	v_cvt_pk_bf16_f32 v152, v152, v152
	v_cvt_pk_bf16_f32 v153, v153, v153
	ds_write_b16 v93, v152
	ds_write_b16 v94, v153
	v_cvt_pk_bf16_f32 v154, v154, v154
	v_cvt_pk_bf16_f32 v155, v155, v155
	ds_write_b16 v96, v154
	ds_write_b16 v97, v155
	v_cvt_pk_bf16_f32 v156, v156, v156
	v_cvt_pk_bf16_f32 v157, v157, v157
	ds_write_b16 v99, v156
	ds_write_b16 v100, v157
	v_cvt_pk_bf16_f32 v158, v158, v158
	v_cvt_pk_bf16_f32 v159, v159, v159
	ds_write_b16 v102, v158
	ds_write_b16 v103, v159
	v_cvt_pk_bf16_f32 v160, v160, v160
	v_cvt_pk_bf16_f32 v161, v161, v161
	ds_write_b16 v105, v160
	ds_write_b16 v106, v161
	s_mov_b64 exec, s[2:3]
	v_cvt_pk_bf16_f32 v162, v162, v162
	v_cvt_pk_bf16_f32 v163, v163, v163
	ds_write_b16 v108, v162
	ds_write_b16 v109, v163
	s_mov_b64 exec, s[44:45]
	s_mov_b32 s44, 0
	s_mov_b64 s[42:43], 0
	v_mov_b32_e32 v0, v111
	s_branch .LBB0_454

; __device__ __forceinline__ void rwkv_chain(LAS unsigned char* lds, int cid, const bf16_t* P0, const float* mu, const float* w0, const float* w2, const float* a0, const float* a2, ...
;     ...
;     if (tid < 64) { const int j = tid, c = h * 64 + j;
;         cst[0 * 64 + j] = a0[c]; cst[1 * 64 + j] = w0[dir * 512 + c]; cst[2 * 64 + j] = k_k[c]; cst[3 * 64 + j] = k_a[c]; cst[4 * 64 + j] = r_k[c];
;         cst[5 * 64 + j] = mu[c]; cst[6 * 64 + j] = mu[512 + c]; cst[7 * 64 + j] = mu[1024 + c]; cst[8 * 64 + j] = mu[1536 + j]; cst[9 * 64 + j] = mu[1600 + j];
;         cst[10 * 64 + j] = (j < 16) ? mu[1664 + h * 16 + j] : 0.f; }
.LBB0_458:
	s_or_b64 exec, exec, s[42:43]
	s_mov_b64 s[10:11], exec
	v_readlane_b32 s2, v253, 42
	v_readlane_b32 s3, v253, 43
	s_and_b64 s[2:3], s[10:11], s[2:3]
	s_mov_b64 exec, s[2:3]
	s_cbranch_execz .LBB0_462
	v_or_b32_e32 v0, s0, v200
	v_lshlrev_b32_e32 v0, 2, v0
	v_lshl_or_b32 v3, s87, 11, v0
	v_mov_b32_e32 v1, v38
	v_mov_b32_e32 v47, v38
	global_load_dword v148, v0, s[40:41]
	global_load_dword v149, v3, s[16:17]
	global_load_dword v150, v0, s[36:37]
	global_load_dword v151, v0, s[38:39]
	global_load_dword v152, v0, s[14:15]
	global_load_dword v153, v0, s[12:13]
	global_load_dword v154, v0, s[12:13] offset:2048
	v_lshl_add_u64 v[2:3], s[12:13], 0, v[0:1]
	s_movk_i32 s2, 0x1000
	v_add_co_u32_e32 v4, vcc, s2, v2
	s_nop 1
	v_addc_co_u32_e32 v5, vcc, 0, v3, vcc
	global_load_dword v155, v[4:5], off
	v_lshl_add_u64 v[4:5], s[12:13], 0, v[46:47]
	v_add_co_u32_e32 v4, vcc, 0x1000, v4
	s_nop 1
	v_addc_co_u32_e32 v5, vcc, 0, v5, vcc
	global_load_dword v156, v[4:5], off offset:2048
	global_load_dword v157, v[4:5], off offset:2304
	v_mov_b32_e32 v158, 0
	s_mov_b64 s[14:15], exec
	v_readlane_b32 s2, v253, 44
	v_readlane_b32 s3, v253, 45
	s_and_b64 s[2:3], s[14:15], s[2:3]
	s_mov_b64 exec, s[2:3]
	s_cbranch_execz .LBB0_461
	v_lshl_or_b32 v4, s1, 6, v85
	v_mov_b32_e32 v5, v38
	v_lshl_add_u64 v[4:5], s[12:13], 0, v[4:5]
	v_add_co_u32_e32 v4, vcc, 0x1000, v4
	s_nop 1
	v_addc_co_u32_e32 v5, vcc, 0, v5, vcc
	global_load_dword v158, v[4:5], off offset:2560
.LBB0_461:
	s_or_b64 exec, exec, s[14:15]
	s_waitcnt vmcnt(0)
	ds_write2st64_b32 v86, v148, v149 offset1:1
	ds_write2st64_b32 v86, v150, v151 offset0:2 offset1:3
	ds_write2st64_b32 v86, v152, v153 offset0:4 offset1:5
	ds_write2st64_b32 v86, v154, v155 offset0:6 offset1:7
	ds_write2st64_b32 v86, v156, v157 offset0:8 offset1:9
	ds_write_b32 v86, v158 offset:2560
